# attention QK^T: K fragments read three key blocks ahead into free registers with counted waits; scan y stores handed to the idle waves
# speedup vs baseline: 1.0114x; 1.0035x over previous
.Latt_p1done:
	s_or_b64 exec, exec, s[68:69]
	ds_read_b128 v[104:107], v157 offset:64
	ds_read_b128 v[100:103], v157
	ds_read_b128 v[252:255], v158 offset:64
	ds_read_b128 v[248:251], v158
	ds_read_b128 v[240:243], v159 offset:64
	ds_read_b128 v[236:239], v159
	s_waitcnt lgkmcnt(4)
	v_mfma_f32_16x16x32_bf16 v[208:211], v[100:103], v[96:99], 0
	v_mfma_f32_16x16x32_bf16 v[208:211], v[104:107], v[92:95], v[208:211]
	ds_read_b128 v[104:107], v160 offset:64
	ds_read_b128 v[100:103], v160
	s_mul_hi_u32 s16, s84, 0xaaaaaaab
	s_lshr_b32 s16, s16, 8
	s_mul_i32 s17, s16, 0x180
	s_sub_i32 s17, s84, s17
	s_waitcnt lgkmcnt(4)
	v_mfma_f32_16x16x32_bf16 v[124:127], v[248:251], v[96:99], 0
	v_mfma_f32_16x16x32_bf16 v[124:127], v[252:255], v[92:95], v[124:127]
	ds_read_b128 v[252:255], v172 offset:64
	ds_read_b128 v[248:251], v172
	s_mul_i32 s19, s17, 0xaaab
	s_lshr_b32 s19, s19, 18
	s_and_b32 s19, s19, 0x3ff8
	s_lshl_b32 s17, s17, 1
	s_waitcnt lgkmcnt(4)
	v_mfma_f32_16x16x32_bf16 v[116:119], v[236:239], v[96:99], 0
	v_mfma_f32_16x16x32_bf16 v[116:119], v[240:243], v[92:95], v[116:119]
	ds_read_b128 v[240:243], v173 offset:64
	ds_read_b128 v[236:239], v173
	s_add_i32 s16, s16, s19
	s_and_b32 s19, s17, 0xfffe
	s_mulk_i32 s19, 0x2aab
	s_lshr_b32 s19, s19, 20
	s_waitcnt lgkmcnt(4)
	v_mfma_f32_16x16x32_bf16 v[108:111], v[100:103], v[96:99], 0
	v_mfma_f32_16x16x32_bf16 v[108:111], v[104:107], v[92:95], v[108:111]
	ds_read_b128 v[104:107], v161 offset:64
	ds_read_b128 v[100:103], v161
	s_mulk_i32 s19, 0x60
	s_sub_i32 s17, s17, s19
	s_mulk_i32 s16, 0x60
	s_and_b32 s17, s17, 0xfffe
	s_waitcnt lgkmcnt(4)
	v_mfma_f32_16x16x32_bf16 v[112:115], v[248:251], v[96:99], 0
	v_mfma_f32_16x16x32_bf16 v[112:115], v[252:255], v[92:95], v[112:115]
	ds_read_b128 v[252:255], v171 offset:64
	ds_read_b128 v[248:251], v171
	s_add_i32 s16, s16, s17
	v_add_u32_e32 v0, s16, v142
	v_mul_hi_u32 v1, v0, s25
	v_lshrrev_b32_e32 v135, 6, v1
	s_waitcnt lgkmcnt(4)
	v_mfma_f32_16x16x32_bf16 v[120:123], v[236:239], v[96:99], 0
	v_mfma_f32_16x16x32_bf16 v[120:123], v[240:243], v[92:95], v[120:123]
	ds_read_b128 v[240:243], v174 offset:64
	ds_read_b128 v[236:239], v174
	v_mul_lo_u32 v1, v135, s24
	v_sub_u32_e32 v0, v0, v1
	v_lshrrev_b32_e32 v131, 5, v0
	v_and_b32_e32 v206, 31, v0
	s_waitcnt lgkmcnt(4)
	v_mfma_f32_16x16x32_bf16 v[100:103], v[100:103], v[96:99], 0
	v_mfma_f32_16x16x32_bf16 v[104:107], v[104:107], v[92:95], v[100:103]
	v_lshlrev_b32_e32 v129, 1, v131
	v_lshrrev_b32_e32 v0, v129, v206
	v_mov_b32_e32 v2, s74
	v_cndmask_b32_e64 v1, v211, v203, s[46:47]
	s_waitcnt lgkmcnt(2)
	v_mfma_f32_16x16x32_bf16 v[100:103], v[248:251], v[96:99], 0
	v_mfma_f32_16x16x32_bf16 v[100:103], v[252:255], v[92:95], v[100:103]
	v_cmp_eq_u32_e64 s[66:67], 0, v0
	s_waitcnt lgkmcnt(0)
	v_mfma_f32_16x16x32_bf16 v[96:99], v[236:239], v[96:99], 0
	v_mfma_f32_16x16x32_bf16 v[92:95], v[240:243], v[92:95], v[96:99]
	s_nop 4
	v_cndmask_b32_e64 v99, v208, v2, s[36:37]
	v_cndmask_b32_e64 v98, v209, v203, s[40:41]
	v_cndmask_b32_e64 v2, v210, v203, s[42:43]
	s_and_saveexec_b64 s[16:17], s[66:67]
	s_cbranch_execz .LBB0_1163
	v_mov_b32_e32 v124, 0xff800000
	v_cndmask_b32_e64 v119, v203, v119, s[50:51]
	v_cndmask_b32_e64 v118, v203, v118, s[50:51]
	v_cndmask_b32_e64 v117, v203, v117, s[50:51]
	v_cndmask_b32_e64 v116, v203, v116, s[50:51]
	v_cndmask_b32_e64 v111, v111, v203, s[52:53]
	v_cndmask_b32_e64 v110, v110, v203, s[52:53]
	v_cndmask_b32_e64 v109, v109, v203, s[52:53]
	v_cndmask_b32_e64 v108, v108, v203, s[52:53]
	v_cndmask_b32_e64 v107, v107, v203, s[54:55]
	v_cndmask_b32_e64 v106, v106, v203, s[54:55]
	v_cndmask_b32_e64 v105, v105, v203, s[54:55]
	v_cndmask_b32_e64 v104, v104, v203, s[54:55]
	v_cndmask_b32_e64 v103, v103, v203, s[56:57]
	v_cndmask_b32_e64 v102, v102, v203, s[56:57]
	v_cndmask_b32_e64 v101, v101, v203, s[56:57]
	v_cndmask_b32_e64 v100, v100, v203, s[56:57]
	v_cndmask_b32_e64 v115, v115, v203, s[58:59]
	v_cndmask_b32_e64 v114, v114, v203, s[58:59]
	v_cndmask_b32_e64 v113, v113, v203, s[58:59]
	v_cndmask_b32_e64 v112, v112, v203, s[58:59]
	v_cndmask_b32_e64 v123, v123, v203, s[58:59]
	v_cndmask_b32_e64 v122, v122, v203, s[58:59]
	v_cndmask_b32_e64 v121, v121, v203, s[58:59]
	v_cndmask_b32_e64 v120, v120, v203, s[58:59]
	v_mov_b32_e32 v125, v124
	v_mov_b32_e32 v126, v124
	v_mov_b32_e32 v127, v124
	v_mov_b32_e32 v99, v124
	v_mov_b32_e32 v98, v124
	v_mov_b32_e32 v2, v124
	v_mov_b32_e32 v1, v124

.LBB0_1165:
	s_or_b64 exec, exec, s[16:17]
	ds_read_b128 v[96:99], v185 offset:64
	ds_read_b128 v[92:95], v185
	ds_read_b128 v[252:255], v186 offset:64
	ds_read_b128 v[248:251], v186
	ds_read_b128 v[240:243], v187 offset:64
	ds_read_b128 v[236:239], v187
	s_waitcnt lgkmcnt(4)
	v_mfma_f32_16x16x32_bf16 v[124:127], v[92:95], v[88:91], 0
	v_mfma_f32_16x16x32_bf16 v[124:127], v[96:99], v[84:87], v[124:127]
	ds_read_b128 v[96:99], v188 offset:64
	ds_read_b128 v[92:95], v188
	v_mov_b32_e32 v0, s74
	s_waitcnt lgkmcnt(4)
	v_mfma_f32_16x16x32_bf16 v[116:119], v[248:251], v[88:91], 0
	v_mfma_f32_16x16x32_bf16 v[116:119], v[252:255], v[84:87], v[116:119]
	ds_read_b128 v[252:255], v189 offset:64
	ds_read_b128 v[248:251], v189
	s_waitcnt lgkmcnt(4)
	v_mfma_f32_16x16x32_bf16 v[112:115], v[236:239], v[88:91], 0
	v_mfma_f32_16x16x32_bf16 v[112:115], v[240:243], v[84:87], v[112:115]
	ds_read_b128 v[240:243], v190 offset:64
	ds_read_b128 v[236:239], v190
	v_cndmask_b32_e64 v2, v124, v0, s[36:37]
	v_cndmask_b32_e64 v1, v126, v203, s[42:43]
	v_cndmask_b32_e64 v0, v127, v203, s[46:47]
	s_waitcnt lgkmcnt(4)
	v_mfma_f32_16x16x32_bf16 v[108:111], v[92:95], v[88:91], 0
	v_mfma_f32_16x16x32_bf16 v[108:111], v[96:99], v[84:87], v[108:111]
	ds_read_b128 v[96:99], v191 offset:64
	ds_read_b128 v[92:95], v191
	s_waitcnt lgkmcnt(4)
	v_mfma_f32_16x16x32_bf16 v[104:107], v[248:251], v[88:91], 0
	v_mfma_f32_16x16x32_bf16 v[104:107], v[252:255], v[84:87], v[104:107]
	ds_read_b128 v[252:255], v192 offset:64
	ds_read_b128 v[248:251], v192
	s_waitcnt lgkmcnt(4)
	v_mfma_f32_16x16x32_bf16 v[100:103], v[236:239], v[88:91], 0
	v_mfma_f32_16x16x32_bf16 v[100:103], v[240:243], v[84:87], v[100:103]
	ds_read_b128 v[240:243], v193 offset:64
	ds_read_b128 v[236:239], v193
	s_waitcnt lgkmcnt(4)
	v_mfma_f32_16x16x32_bf16 v[92:95], v[92:95], v[88:91], 0
	v_mfma_f32_16x16x32_bf16 v[92:95], v[96:99], v[84:87], v[92:95]
	s_waitcnt lgkmcnt(2)
	v_mfma_f32_16x16x32_bf16 v[96:99], v[248:251], v[88:91], 0
	v_mfma_f32_16x16x32_bf16 v[96:99], v[252:255], v[84:87], v[96:99]
	s_waitcnt lgkmcnt(0)
	v_mfma_f32_16x16x32_bf16 v[88:91], v[236:239], v[88:91], 0
	v_mfma_f32_16x16x32_bf16 v[84:87], v[240:243], v[84:87], v[88:91]
	s_nop 4
	v_cndmask_b32_e64 v91, v125, v203, s[40:41]
	s_and_saveexec_b64 s[16:17], s[66:67]
	s_cbranch_execz .LBB0_1167
	v_cndmask_b32_e64 v119, v203, v119, s[50:51]
	v_cndmask_b32_e64 v118, v203, v118, s[50:51]
	v_cndmask_b32_e64 v117, v203, v117, s[50:51]
	v_cndmask_b32_e64 v116, v203, v116, s[50:51]
	v_cndmask_b32_e64 v115, v203, v115, s[50:51]
	v_cndmask_b32_e64 v114, v203, v114, s[50:51]
	v_cndmask_b32_e64 v113, v203, v113, s[50:51]
	v_cndmask_b32_e64 v112, v203, v112, s[50:51]
	v_cndmask_b32_e64 v111, v111, v203, s[62:63]
	v_cndmask_b32_e64 v110, v110, v203, s[62:63]
	v_cndmask_b32_e64 v109, v109, v203, s[62:63]
	v_cndmask_b32_e64 v108, v108, v203, s[62:63]
	v_cndmask_b32_e64 v107, v107, v203, s[54:55]
	v_cndmask_b32_e64 v106, v106, v203, s[54:55]
	v_cndmask_b32_e64 v105, v105, v203, s[54:55]
	v_cndmask_b32_e64 v104, v104, v203, s[54:55]
	v_cndmask_b32_e64 v103, v103, v203, s[64:65]
	v_cndmask_b32_e64 v102, v102, v203, s[64:65]
	v_cndmask_b32_e64 v101, v101, v203, s[64:65]
	v_cndmask_b32_e64 v100, v100, v203, s[64:65]
	v_cndmask_b32_e64 v95, v95, v203, s[58:59]
	v_cndmask_b32_e64 v94, v94, v203, s[58:59]
	v_cndmask_b32_e64 v93, v93, v203, s[58:59]
	v_cndmask_b32_e64 v92, v92, v203, s[58:59]
	v_mov_b32_e32 v2, 0xff800000
	v_mov_b32_e32 v91, 0xff800000
	v_mov_b32_e32 v1, 0xff800000
	v_mov_b32_e32 v0, 0xff800000

	.amdhsa_kernel _Z14fwd_megakernel6Params
		.amdhsa_group_segment_fixed_size 0
		.amdhsa_private_segment_fixed_size 0
		.amdhsa_kernarg_size 456
		.amdhsa_user_sgpr_count 2
		.amdhsa_user_sgpr_dispatch_ptr 0
		.amdhsa_user_sgpr_queue_ptr 0
		.amdhsa_user_sgpr_kernarg_segment_ptr 1
		.amdhsa_user_sgpr_dispatch_id 0
		.amdhsa_user_sgpr_kernarg_preload_length 0
		.amdhsa_user_sgpr_kernarg_preload_offset 0
		.amdhsa_user_sgpr_private_segment_size 0
		.amdhsa_uses_dynamic_stack 0
		.amdhsa_enable_private_segment 0
		.amdhsa_system_sgpr_workgroup_id_x 1
		.amdhsa_system_sgpr_workgroup_id_y 0
		.amdhsa_system_sgpr_workgroup_id_z 0
		.amdhsa_system_sgpr_workgroup_info 0
		.amdhsa_system_vgpr_workitem_id 2
		.amdhsa_next_free_vgpr 256
		.amdhsa_next_free_sgpr 100
		.amdhsa_accum_offset 256
		.amdhsa_reserve_vcc 1
		.amdhsa_float_round_mode_32 0
		.amdhsa_float_round_mode_16_64 0
		.amdhsa_float_denorm_mode_32 3
		.amdhsa_float_denorm_mode_16_64 3
		.amdhsa_dx10_clamp 1
		.amdhsa_ieee_mode 1
		.amdhsa_fp16_overflow 0
		.amdhsa_tg_split 0
		.amdhsa_exception_fp_ieee_invalid_op 0
		.amdhsa_exception_fp_denorm_src 0
		.amdhsa_exception_fp_ieee_div_zero 0
		.amdhsa_exception_fp_ieee_overflow 0
		.amdhsa_exception_fp_ieee_underflow 0
		.amdhsa_exception_fp_ieee_inexact 0
		.amdhsa_exception_int_div_zero 0
	.end_amdhsa_kernel

amdhsa.kernels:
  - .agpr_count:     0
    .args:
      - .offset:         0
        .size:           200
        .value_kind:     by_value
      - .offset:         200
        .size:           4
        .value_kind:     hidden_block_count_x
      - .offset:         204
        .size:           4
        .value_kind:     hidden_block_count_y
      - .offset:         208
        .size:           4
        .value_kind:     hidden_block_count_z
      - .offset:         212
        .size:           2
        .value_kind:     hidden_group_size_x
      - .offset:         214
        .size:           2
        .value_kind:     hidden_group_size_y
      - .offset:         216
        .size:           2
        .value_kind:     hidden_group_size_z
      - .offset:         218
        .size:           2
        .value_kind:     hidden_remainder_x
      - .offset:         220
        .size:           2
        .value_kind:     hidden_remainder_y
      - .offset:         222
        .size:           2
        .value_kind:     hidden_remainder_z
      - .offset:         240
        .size:           8
        .value_kind:     hidden_global_offset_x
      - .offset:         248
        .size:           8
        .value_kind:     hidden_global_offset_y
      - .offset:         256
        .size:           8
        .value_kind:     hidden_global_offset_z
      - .offset:         264
        .size:           2
        .value_kind:     hidden_grid_dims
      - .offset:         288
        .size:           8
        .value_kind:     hidden_multigrid_sync_arg
      - .offset:         320
        .size:           4
        .value_kind:     hidden_dynamic_lds_size
    .group_segment_fixed_size: 0
    .kernarg_segment_align: 8
    .kernarg_segment_size: 456
    .language:       OpenCL C
    .language_version:
      - 2
      - 0
    .max_flat_workgroup_size: 512
    .name:           _Z14fwd_megakernel6Params
    .private_segment_fixed_size: 0
    .sgpr_count:     106
    .sgpr_spill_count: 48
    .symbol:         _Z14fwd_megakernel6Params.kd
    .uniform_work_group_size: 1
    .uses_dynamic_stack: false
    .vgpr_count:     256
    .vgpr_spill_count: 0
    .wavefront_size: 64
